# retention loop: v_pk_mul/fma_f32 split into scalar f32 ops (on v014)
# speedup vs baseline: 1.0217x; 1.0217x over previous
.LBB0_1370:
	s_add_i32 s1, s57, -1
	s_waitcnt vmcnt(7)
	ds_write_b128 v175, v[72:75]
	ds_write_b128 v175, v[68:71] offset:8704
	ds_write_b128 v175, v[64:67] offset:17408
	v_cndmask_b32_e32 v65, v180, v173, vcc
	v_xor_b32_e32 v66, 0xffffffef, v173
	v_xor_b32_e32 v70, 0xffffffcf, v173
	s_min_u32 s18, s1, s0
	v_add_u32_e32 v69, 48, v173
	v_xor_b32_e32 v67, 0xffffffdf, v173
	v_add_u32_e32 v71, s55, v66
	v_add_u32_e32 v66, s56, v65
	v_add_u32_e32 v70, s55, v70
	v_lshl_add_u32 v73, s18, 5, v174
	v_add_u32_e32 v64, 16, v173
	v_add_u32_e32 v68, 32, v173
	v_add_u32_e32 v65, s55, v67
	v_ashrrev_i32_e32 v67, 31, v66
	v_cndmask_b32_e32 v69, v70, v69, vcc
	v_xad_u32 v70, v73, -1, s55
	v_cndmask_b32_e32 v71, v71, v64, vcc
	v_cndmask_b32_e32 v68, v65, v68, vcc
	v_lshlrev_b64 v[64:65], 11, v[66:67]
	v_cndmask_b32_e32 v67, v70, v73, vcc
	s_min_u32 s42, s57, s0
	v_lshl_add_u64 v[242:243], v[170:171], 0, v[64:65]
	v_add_u32_e32 v64, s56, v67
	v_lshl_add_u32 v72, s42, 5, v174
	v_ashrrev_i32_e32 v65, 31, v64
	v_cvt_pk_bf16_f32 v60, v44, v45
	v_cvt_pk_bf16_f32 v61, v46, v47
	v_cvt_pk_bf16_f32 v62, v40, v41
	v_cvt_pk_bf16_f32 v63, v42, v43
	v_xad_u32 v74, v72, -1, s55
	v_lshlrev_b64 v[64:65], 13, v[64:65]
	v_cndmask_b32_e32 v66, v74, v72, vcc
	v_or_b32_e32 v64, v64, v181
	v_add_u32_e32 v238, s56, v68
	v_add_u32_e32 v240, s56, v69
	v_add_u32_e32 v244, s56, v66
	v_lshl_add_u64 v[66:67], s[36:37], 0, v[64:65]
	v_lshl_add_u64 v[68:69], s[38:39], 0, v[64:65]
	v_lshl_add_u64 v[64:65], s[40:41], 0, v[64:65]
	v_add_u32_e32 v0, 0x1000, v178
	v_add_u32_e32 v1, 0x2000, v179
	v_add_u32_e32 v182, 0x3000, v179
	v_add_u32_e32 v236, s56, v71
	global_load_dwordx4 v[72:75], v[66:67], off
	s_nop 0
	global_load_dwordx4 v[68:71], v[68:69], off
	s_nop 0
	global_load_dwordx4 v[64:67], v[64:65], off
	s_waitcnt lgkmcnt(0)
	s_barrier
	ds_read_b64 v[188:189], v178
	ds_read_b64 v[190:191], v178 offset:32
	ds_read_b64 v[192:193], v0 offset:256
	ds_read_b64 v[194:195], v0 offset:288
	ds_read_b64 v[196:197], v0 offset:320
	ds_read_b64 v[198:199], v0 offset:352
	ds_read_b64 v[200:201], v1 offset:512
	ds_read_b64 v[202:203], v1 offset:544
	ds_read_b64 v[204:205], v182 offset:768
	ds_read_b64 v[206:207], v182 offset:800
	ds_read_b64_tr_b16 v[210:211], v176 offset:13056
	ds_read_b64_tr_b16 v[212:213], v177 offset:17408
	ds_read_b64_tr_b16 v[214:215], v177 offset:21760
	ds_read_b64_tr_b16 v[208:209], v176 offset:8704
	ds_read_b64_tr_b16 v[216:217], v176 offset:8736
	ds_read_b64_tr_b16 v[220:221], v176 offset:8768
	ds_read_b64_tr_b16 v[222:223], v176 offset:13120
	ds_read_b64_tr_b16 v[218:219], v176 offset:13088
	ds_read_b64_tr_b16 v[230:231], v176 offset:8928
	s_waitcnt lgkmcnt(7)
	v_lshlrev_b32_e32 v232, 16, v212
	v_and_b32_e32 v233, 0xffff0000, v212
	v_lshlrev_b32_e32 v234, 16, v213
	v_and_b32_e32 v235, 0xffff0000, v213
	s_waitcnt lgkmcnt(6)
	v_lshlrev_b32_e32 v246, 16, v214
	v_and_b32_e32 v247, 0xffff0000, v214
	v_lshlrev_b32_e32 v248, 16, v215
	v_and_b32_e32 v249, 0xffff0000, v215
	v_mov_b32_e32 v159, v158
	v_mfma_f32_16x16x32_bf16 v[226:229], v[60:63], v[192:195], 0
	v_mul_f32_e64 v232, v150, v232
	v_mul_f32_e64 v233, v151, v233
	v_mul_f32_e32 v234, v152, v234
	v_mul_f32_e32 v235, v153, v235
	v_mul_f32_e32 v44, v164, v44
	v_mul_f32_e32 v45, v165, v45
	v_mfma_f32_16x16x32_bf16 v[60:63], v[60:63], v[188:191], 0
	v_mul_f32_e64 v46, v158, v46
	v_mul_f32_e64 v47, v159, v47
	v_mul_f32_e32 v40, v164, v40
	v_mul_f32_e32 v41, v165, v41
	v_mul_f32_e32 v42, v158, v42
	v_mul_f32_e32 v43, v159, v43
	v_mfma_f32_16x16x32_bf16 v[188:191], v[200:203], v[188:191], 0
	v_cvt_pk_bf16_f32 v52, v36, v37
	v_cvt_pk_bf16_f32 v53, v38, v39
	v_cvt_pk_bf16_f32 v54, v32, v33
	v_mfma_f32_16x16x32_bf16 v[200:203], v[200:203], v[192:195], 0
	v_cvt_pk_bf16_f32 v55, v34, v35
	v_cvt_pk_bf16_f32 v56, v28, v29
	v_cvt_pk_bf16_f32 v57, v30, v31
	v_mfma_f32_16x16x32_bf16 v[192:195], v[204:207], v[192:195], 0
	v_mul_f32_e64 v206, v154, v246
	v_mul_f32_e64 v207, v155, v247
	v_mul_f32_e32 v246, v156, v248
	v_mul_f32_e32 v247, v157, v249
	v_cvt_pk_bf16_f32 v204, v232, v233
	v_cvt_pk_bf16_f32 v205, v234, v235
	v_cvt_pk_bf16_f32 v206, v206, v207
	v_cvt_pk_bf16_f32 v207, v246, v247
	v_mul_f32_e32 v36, v164, v36
	v_mul_f32_e32 v37, v165, v37
	v_mul_f32_e32 v32, v164, v32
	v_mul_f32_e32 v33, v165, v33
	s_waitcnt lgkmcnt(5)
	v_mfma_f32_16x16x32_bf16 v[44:47], v[208:211], v[204:207], v[44:47]
	ds_read_b64_tr_b16 v[210:211], v176 offset:13152
	ds_read_b64_tr_b16 v[208:209], v176 offset:8800
	ds_read_b64_tr_b16 v[232:233], v176 offset:8832
	v_mul_f32_e32 v28, v164, v28
	v_mul_f32_e32 v29, v165, v29
	v_mul_f32_e32 v38, v158, v38
	v_mul_f32_e32 v39, v159, v39
	s_waitcnt lgkmcnt(4)
	v_mfma_f32_16x16x32_bf16 v[40:43], v[216:219], v[204:207], v[40:43]
	ds_read_b64_tr_b16 v[216:217], v176 offset:8864
	ds_read_b64_tr_b16 v[234:235], v176 offset:13184
	ds_read_b64_tr_b16 v[218:219], v176 offset:13216
	v_mul_f32_e32 v34, v158, v34
	v_mul_f32_e32 v35, v159, v35
	v_mul_f32_e32 v30, v158, v30
	v_mul_f32_e32 v31, v159, v31
	v_mfma_f32_16x16x32_bf16 v[36:39], v[220:223], v[204:207], v[36:39]
	v_ashrrev_i32_e32 v245, 31, v244
	v_ashrrev_i32_e32 v237, 31, v236
	v_cvt_pk_bf16_f32 v58, v24, v25
	s_waitcnt lgkmcnt(4)
	v_mfma_f32_16x16x32_bf16 v[32:35], v[208:211], v[204:207], v[32:35]
	ds_read_b64_tr_b16 v[208:209], v176 offset:8896
	ds_read_b64_tr_b16 v[210:211], v176 offset:13248
	v_cvt_pk_bf16_f32 v59, v26, v27
	s_waitcnt lgkmcnt(3)
	v_mfma_f32_16x16x32_bf16 v[220:223], v[232:235], v[204:207], v[28:31]
	ds_read_b64_tr_b16 v[232:233], v176 offset:13280
	v_cvt_pk_bf16_f32 v48, v20, v21
	v_cvt_pk_bf16_f32 v49, v22, v23
	v_lshlrev_b64 v[28:29], 13, v[244:245]
	v_cvt_pk_bf16_f32 v50, v16, v17
	v_cvt_pk_bf16_f32 v51, v18, v19
	v_mul_f32_e32 v24, v164, v24
	v_mul_f32_e32 v25, v165, v25
	v_mul_f32_e32 v20, v164, v20
	v_mul_f32_e32 v21, v165, v21
	v_mul_f32_e32 v16, v164, v16
	v_mul_f32_e32 v17, v165, v17
	v_mul_f32_e32 v26, v158, v26
	v_mul_f32_e32 v27, v159, v27
	v_mul_f32_e32 v22, v158, v22
	v_mul_f32_e32 v23, v159, v23
	v_mul_f32_e32 v18, v158, v18
	v_mul_f32_e32 v19, v159, v19
	v_ashrrev_i32_e32 v239, 31, v238
	v_ashrrev_i32_e32 v241, 31, v240
	v_lshlrev_b64 v[236:237], 11, v[236:237]
	v_or_b32_e32 v28, v28, v181
	v_lshlrev_b64 v[246:247], 11, v[238:239]
	v_lshlrev_b64 v[248:249], 11, v[240:241]
	s_waitcnt lgkmcnt(3)
	v_mfma_f32_16x16x32_bf16 v[216:219], v[216:219], v[204:207], v[24:27]
	v_lshl_add_u64 v[234:235], v[170:171], 0, v[236:237]
	v_lshl_add_u64 v[236:237], s[36:37], 0, v[28:29]
	v_lshl_add_u64 v[238:239], s[38:39], 0, v[28:29]
	s_waitcnt lgkmcnt(1)
	v_mfma_f32_16x16x32_bf16 v[208:211], v[208:211], v[204:207], v[20:23]
	ds_read_b64 v[24:25], v1 offset:576
	ds_read_b64 v[26:27], v1 offset:608
	v_lshl_add_u64 v[240:241], s[40:41], 0, v[28:29]
	ds_read_b64 v[28:29], v182 offset:832
	ds_read_b64 v[30:31], v182 offset:864
	s_waitcnt lgkmcnt(4)
	v_mfma_f32_16x16x32_bf16 v[204:207], v[230:233], v[204:207], v[16:19]
	v_mov_b32_e32 v3, v2
	v_add_u32_e32 v183, 0x6000, v178
	v_add_u32_e32 v184, 0x7000, v178
	ds_read_b64 v[16:17], v178 offset:64
	ds_read_b64 v[18:19], v178 offset:96
	v_mfma_f32_16x16x32_bf16 v[226:229], v[52:55], v[196:199], v[226:229]
	v_add_u32_e32 v185, 0x8800, v179
	v_add_u32_e32 v186, 0x9800, v179
	s_add_i32 s57, s57, 2
	s_waitcnt lgkmcnt(0)
	v_mfma_f32_16x16x32_bf16 v[20:23], v[52:55], v[16:19], v[60:63]
	ds_read_b64 v[52:53], v0 offset:384
	ds_read_b64 v[54:55], v0 offset:416
	s_nop 1
	ds_read_b64 v[60:61], v178 offset:128
	ds_read_b64 v[62:63], v178 offset:160
	v_add_u32_e32 v173, 64, v173
	v_subrev_u32_e32 v180, 64, v180
	v_mfma_f32_16x16x32_bf16 v[16:19], v[24:27], v[16:19], v[188:191]
	s_cmp_ge_u32 s1, s58
	v_mfma_f32_16x16x32_bf16 v[24:27], v[24:27], v[196:199], v[200:203]
	v_mfma_f32_16x16x32_bf16 v[28:31], v[28:31], v[196:199], v[192:195]
	s_nop 2
	ds_read_b64 v[192:193], v1 offset:640
	ds_read_b64 v[194:195], v1 offset:672
	ds_read_b64 v[196:197], v178 offset:192
	ds_read_b64 v[198:199], v178 offset:224
	ds_read_b64 v[200:201], v0 offset:448
	ds_read_b64 v[202:203], v0 offset:480
	s_waitcnt lgkmcnt(8)
	v_mfma_f32_16x16x32_bf16 v[188:191], v[56:59], v[52:55], v[226:229]
	s_waitcnt lgkmcnt(6)
	v_mfma_f32_16x16x32_bf16 v[20:23], v[56:59], v[60:63], v[20:23]
	ds_read_b64 v[56:57], v182 offset:896
	ds_read_b64 v[58:59], v182 offset:928
	ds_read_b64 v[226:227], v1 offset:704
	ds_read_b64 v[228:229], v1 offset:736
	ds_read_b64 v[230:231], v182 offset:960
	ds_read_b64 v[232:233], v182 offset:992
	s_waitcnt vmcnt(5)
	ds_write_b128 v175, v[12:15] offset:26112
	ds_write_b128 v175, v[8:11] offset:34816
	ds_write_b128 v175, v[4:7] offset:43520
	s_waitcnt lgkmcnt(13)
	v_mfma_f32_16x16x32_bf16 v[16:19], v[192:195], v[60:63], v[16:19]
	v_mfma_f32_16x16x32_bf16 v[4:7], v[192:195], v[52:55], v[24:27]
	s_waitcnt lgkmcnt(7)
	v_mfma_f32_16x16x32_bf16 v[8:11], v[56:59], v[52:55], v[28:31]
	s_nop 0
	v_cvt_pk_bf16_f32 v24, v44, v45
	v_cvt_pk_bf16_f32 v25, v46, v47
	v_cvt_pk_bf16_f32 v26, v40, v41
	s_waitcnt lgkmcnt(5)
	v_mfma_f32_16x16x32_bf16 v[16:19], v[226:229], v[196:199], v[16:19]
	v_mul_f32_e64 v28, v164, v44
	v_mul_f32_e64 v29, v165, v45
	v_cvt_pk_bf16_f32 v27, v42, v43
	v_mul_f32_e32 v30, v158, v46
	v_mul_f32_e32 v31, v159, v47
	v_mfma_f32_16x16x32_bf16 v[4:7], v[226:229], v[200:203], v[4:7]
	v_cvt_pk_bf16_f32 v52, v36, v37
	s_nop 1
	v_mul_f32_e32 v18, v146, v18
	v_mul_f32_e32 v19, v147, v19
	v_mul_f32_e32 v0, v142, v16
	v_mul_f32_e32 v1, v143, v17
	s_waitcnt lgkmcnt(3)
	v_mfma_f32_16x16x32_bf16 v[8:11], v[230:233], v[200:203], v[8:11]
	v_cvt_pk_bf16_f32 v0, v0, v1
	v_mul_f32_e32 v6, v148, v6
	v_mul_f32_e32 v7, v149, v7
	v_mul_f32_e32 v4, v144, v4
	v_mul_f32_e32 v5, v145, v5
	v_cvt_pk_bf16_f32 v1, v18, v19
	v_cvt_pk_bf16_f32 v4, v4, v5
	s_nop 2
	v_mul_f32_e32 v16, v146, v10
	v_mul_f32_e32 v17, v147, v11
	v_mul_f32_e32 v44, v142, v8
	v_mul_f32_e32 v45, v143, v9
	v_cvt_pk_bf16_f32 v5, v6, v7
	v_cvt_pk_bf16_f32 v6, v44, v45
	v_cvt_pk_bf16_f32 v7, v16, v17
	v_mfma_f32_16x16x32_bf16 v[12:15], v[48:51], v[200:203], v[188:191]
	v_cvt_pk_bf16_f32 v53, v38, v39
	v_mul_f32_e32 v38, v158, v38
	v_mul_f32_e32 v39, v159, v39
	v_mul_f32_e32 v36, v164, v36
	v_mul_f32_e32 v37, v165, v37
	v_mfma_f32_16x16x32_bf16 v[20:23], v[48:51], v[196:199], v[20:23]
	v_cvt_pk_bf16_f32 v54, v32, v33
	v_cvt_pk_bf16_f32 v55, v34, v35
	v_mul_f32_e32 v42, v158, v42
	v_mul_f32_e32 v43, v159, v43
	v_mfma_f32_16x16x32_bf16 v[8:11], v[212:215], v[0:3], 0
	v_mul_f32_e64 v40, v164, v40
	v_mul_f32_e64 v41, v165, v41
	v_mul_f32_e32 v34, v158, v34
	v_mul_f32_e32 v35, v159, v35
	v_mul_f32_e32 v32, v164, v32
	v_mul_f32_e32 v33, v165, v33
	v_mfma_f32_16x16x32_bf16 v[4:7], v[212:215], v[4:7], 0
	v_mul_f32_e64 v50, v158, v222
	v_mul_f32_e64 v51, v159, v223
	s_nop 0
	v_fmac_f32_e32 v8, v162, v20
	v_fmac_f32_e32 v9, v163, v21
	v_mul_f32_e32 v48, v164, v220
	v_mul_f32_e32 v49, v165, v221
	v_cvt_pk_bf16_f32 v8, v8, v9
	v_cvt_pk_bf16_f32 v56, v220, v221
	s_nop 0
	v_fma_f32 v0, v166, v14, v6
	v_fma_f32 v1, v167, v15, v7
	v_fma_f32 v6, v168, v22, v10
	v_fma_f32 v7, v169, v23, v11
	v_fmac_f32_e32 v4, v160, v12
	v_fmac_f32_e32 v5, v161, v13
	v_cvt_pk_bf16_f32 v9, v6, v7
	v_cvt_pk_bf16_f32 v4, v4, v5
	v_cvt_pk_bf16_f32 v5, v0, v1
	global_store_dwordx2 v[242:243], v[8:9], off
	global_store_dwordx2 v[234:235], v[4:5], off
	global_load_dwordx4 v[12:15], v[236:237], off
	s_nop 0
	global_load_dwordx4 v[8:11], v[238:239], off
	global_load_dwordx4 v[4:7], v[240:241], off
	s_waitcnt lgkmcnt(0)
	s_barrier
	ds_read_b64 v[16:17], v183 offset:1536
	ds_read_b64 v[18:19], v183 offset:1568
	ds_read_b64 v[20:21], v184 offset:1792
	ds_read_b64 v[22:23], v184 offset:1824
	ds_read_b64 v[60:61], v184 offset:1856
	ds_read_b64 v[62:63], v184 offset:1888
	ds_read_b64 v[44:45], v185
	ds_read_b64 v[46:47], v185 offset:32
	ds_read_b64 v[188:189], v186 offset:256
	ds_read_b64 v[190:191], v186 offset:288
	ds_read_b64_tr_b16 v[194:195], v176 offset:39168
	ds_read_b64_tr_b16 v[196:197], v177 offset:43520
	ds_read_b64_tr_b16 v[198:199], v177 offset:47872
	ds_read_b64_tr_b16 v[192:193], v176 offset:34816
	ds_read_b64_tr_b16 v[200:201], v176 offset:34848
	ds_read_b64_tr_b16 v[212:213], v176 offset:34880
	ds_read_b64_tr_b16 v[214:215], v176 offset:39232
	s_waitcnt lgkmcnt(13)
	v_mfma_f32_16x16x32_bf16 v[226:229], v[24:27], v[20:23], 0
	s_waitcnt lgkmcnt(5)
	v_lshlrev_b32_e32 v0, 16, v196
	v_and_b32_e32 v1, 0xffff0000, v196
	v_mul_f32_e32 v0, v150, v0
	v_mul_f32_e32 v1, v151, v1
	v_mfma_f32_16x16x32_bf16 v[234:237], v[24:27], v[16:19], 0
	v_lshlrev_b32_e32 v24, 16, v197
	v_and_b32_e32 v25, 0xffff0000, v197
	v_mul_f32_e32 v24, v152, v24
	v_mul_f32_e32 v25, v153, v25
	v_mfma_f32_16x16x32_bf16 v[238:241], v[44:47], v[16:19], 0
	s_waitcnt lgkmcnt(4)
	v_lshlrev_b32_e32 v16, 16, v198
	v_and_b32_e32 v17, 0xffff0000, v198
	v_lshlrev_b32_e32 v18, 16, v199
	v_and_b32_e32 v19, 0xffff0000, v199
	v_mfma_f32_16x16x32_bf16 v[242:245], v[44:47], v[20:23], 0
	ds_read_b64_tr_b16 v[202:203], v176 offset:39200
	ds_read_b64_tr_b16 v[230:231], v176 offset:35040
	v_cvt_pk_bf16_f32 v57, v222, v223
	v_cvt_pk_bf16_f32 v58, v216, v217
	v_mfma_f32_16x16x32_bf16 v[188:191], v[188:191], v[20:23], 0
	v_mul_f32_e64 v20, v154, v16
	v_mul_f32_e64 v21, v155, v17
	v_mul_f32_e32 v22, v156, v18
	v_mul_f32_e32 v23, v157, v19
	v_cvt_pk_bf16_f32 v16, v0, v1
	v_cvt_pk_bf16_f32 v17, v24, v25
	v_cvt_pk_bf16_f32 v18, v20, v21
	v_cvt_pk_bf16_f32 v19, v22, v23
	ds_read_b64_tr_b16 v[22:23], v176 offset:39264
	ds_read_b64_tr_b16 v[20:21], v176 offset:34912
	ds_read_b64_tr_b16 v[24:25], v176 offset:34944
	s_waitcnt lgkmcnt(8)
	v_mfma_f32_16x16x32_bf16 v[44:47], v[192:195], v[16:19], v[28:31]
	ds_read_b64_tr_b16 v[192:193], v176 offset:34976
	ds_read_b64_tr_b16 v[26:27], v176 offset:39296
	ds_read_b64_tr_b16 v[194:195], v176 offset:39328
	ds_read_b64_tr_b16 v[232:233], v176 offset:39392
	v_cvt_pk_bf16_f32 v59, v218, v219
	s_waitcnt lgkmcnt(9)
	v_mfma_f32_16x16x32_bf16 v[36:39], v[212:215], v[16:19], v[36:39]
	ds_read_b64_tr_b16 v[212:213], v176 offset:35008
	ds_read_b64_tr_b16 v[214:215], v176 offset:39360
	s_waitcnt lgkmcnt(10)
	v_mfma_f32_16x16x32_bf16 v[40:43], v[200:203], v[16:19], v[40:43]
	v_mul_f32_e64 v202, v158, v218
	v_mul_f32_e64 v203, v159, v219
	v_mul_f32_e32 v200, v164, v216
	v_mul_f32_e32 v201, v165, v217
	ds_read_b64 v[216:217], v183 offset:1664
	ds_read_b64 v[218:219], v183 offset:1696
	s_waitcnt lgkmcnt(9)
	v_mfma_f32_16x16x32_bf16 v[32:35], v[20:23], v[16:19], v[32:35]
	v_mul_f32_e64 v22, v158, v210
	v_mul_f32_e64 v23, v159, v211
	v_mul_f32_e32 v20, v164, v208
	v_mul_f32_e32 v21, v165, v209
	s_waitcnt lgkmcnt(6)
	v_mfma_f32_16x16x32_bf16 v[28:31], v[24:27], v[16:19], v[48:51]
	s_waitcnt lgkmcnt(5)
	v_mfma_f32_16x16x32_bf16 v[24:27], v[192:195], v[16:19], v[200:203]
	ds_read_b64 v[192:193], v185 offset:64
	ds_read_b64 v[194:195], v185 offset:96
	v_mul_f32_e32 v50, v158, v206
	v_mul_f32_e32 v51, v159, v207
	v_mul_f32_e32 v48, v164, v204
	v_mul_f32_e32 v49, v165, v205
	s_waitcnt lgkmcnt(4)
	v_mfma_f32_16x16x32_bf16 v[20:23], v[212:215], v[16:19], v[20:23]
	ds_read_b64 v[212:213], v186 offset:320
	ds_read_b64 v[214:215], v186 offset:352
	v_cvt_pk_bf16_f32 v202, v204, v205
	v_cvt_pk_bf16_f32 v203, v206, v207
	v_mfma_f32_16x16x32_bf16 v[16:19], v[230:233], v[16:19], v[48:51]
	ds_read_b64 v[204:205], v183 offset:1728
	ds_read_b64 v[206:207], v183 offset:1760
	v_cvt_pk_bf16_f32 v200, v208, v209
	v_cvt_pk_bf16_f32 v201, v210, v211
	ds_read_b64 v[48:49], v183 offset:1600
	ds_read_b64 v[50:51], v183 offset:1632
	v_mfma_f32_16x16x32_bf16 v[226:229], v[52:55], v[60:63], v[226:229]
	s_waitcnt lgkmcnt(0)
	v_mfma_f32_16x16x32_bf16 v[52:55], v[52:55], v[48:51], v[234:237]
	v_mfma_f32_16x16x32_bf16 v[48:51], v[192:195], v[48:51], v[238:241]
	v_mfma_f32_16x16x32_bf16 v[192:195], v[192:195], v[60:63], v[242:245]
	v_mfma_f32_16x16x32_bf16 v[60:63], v[212:215], v[60:63], v[188:191]
	s_nop 2
	ds_read_b64 v[188:189], v184 offset:1920
	ds_read_b64 v[190:191], v184 offset:1952
	s_waitcnt lgkmcnt(0)
	v_mfma_f32_16x16x32_bf16 v[212:215], v[56:59], v[188:191], v[226:229]
	v_mfma_f32_16x16x32_bf16 v[52:55], v[56:59], v[216:219], v[52:55]
	ds_read_b64 v[56:57], v185 offset:128
	ds_read_b64 v[58:59], v185 offset:160
	s_waitcnt lgkmcnt(0)
	v_mfma_f32_16x16x32_bf16 v[48:51], v[56:59], v[216:219], v[48:51]
	v_mfma_f32_16x16x32_bf16 v[56:59], v[56:59], v[188:191], v[192:195]
	s_nop 2
	ds_read_b64 v[192:193], v186 offset:384
	ds_read_b64 v[194:195], v186 offset:416
	s_waitcnt lgkmcnt(0)
	v_mfma_f32_16x16x32_bf16 v[60:63], v[192:195], v[188:191], v[60:63]
	ds_read_b64 v[188:189], v184 offset:1984
	ds_read_b64 v[190:191], v184 offset:2016
	ds_read_b64 v[182:183], v185 offset:192
	ds_read_b64 v[184:185], v185 offset:224
	s_waitcnt lgkmcnt(0)
	v_mfma_f32_16x16x32_bf16 v[48:51], v[182:185], v[204:207], v[48:51]
	s_nop 7
	v_mul_f32_e32 v50, v146, v50
	v_mul_f32_e32 v51, v147, v51
	v_mfma_f32_16x16x32_bf16 v[56:59], v[182:185], v[188:191], v[56:59]
	ds_read_b64 v[182:183], v186 offset:448
	ds_read_b64 v[184:185], v186 offset:480
	v_mul_f32_e32 v0, v142, v48
	v_mul_f32_e32 v1, v143, v49
	s_waitcnt lgkmcnt(0)
	v_mfma_f32_16x16x32_bf16 v[60:63], v[182:185], v[188:191], v[60:63]
	s_nop 3
	v_mul_f32_e64 v182, v148, v58
	v_mul_f32_e64 v183, v149, v59
	v_mul_f32_e32 v48, v144, v56
	v_mul_f32_e32 v49, v145, v57
	v_cvt_pk_bf16_f32 v0, v0, v1
	v_mul_f32_e32 v62, v146, v62
	v_mul_f32_e32 v63, v147, v63
	v_mul_f32_e32 v60, v142, v60
	v_mul_f32_e32 v61, v143, v61
	v_cvt_pk_bf16_f32 v1, v50, v51
	v_cvt_pk_bf16_f32 v48, v48, v49
	v_cvt_pk_bf16_f32 v49, v182, v183
	v_cvt_pk_bf16_f32 v50, v60, v61
	v_cvt_pk_bf16_f32 v51, v62, v63
	v_mfma_f32_16x16x32_bf16 v[192:195], v[200:203], v[188:191], v[212:215]
	v_mfma_f32_16x16x32_bf16 v[52:55], v[200:203], v[204:207], v[52:55]
	v_lshl_add_u64 v[200:201], v[170:171], 0, v[246:247]
	v_lshl_add_u64 v[202:203], v[170:171], 0, v[248:249]
	v_mfma_f32_16x16x32_bf16 v[56:59], v[196:199], v[0:3], 0
	v_mfma_f32_16x16x32_bf16 v[48:51], v[196:199], v[48:51], 0
	s_nop 6
	v_fma_f32 v52, v162, v52, v56
	v_fma_f32 v53, v163, v53, v57
	v_fma_f32 v0, v166, v194, v50
	v_fma_f32 v1, v167, v195, v51
	v_fma_f32 v50, v168, v54, v58
	v_fma_f32 v51, v169, v55, v59
	v_fmac_f32_e32 v48, v160, v192
	v_fmac_f32_e32 v49, v161, v193
	v_cvt_pk_bf16_f32 v52, v52, v53
	v_cvt_pk_bf16_f32 v53, v50, v51
	v_cvt_pk_bf16_f32 v48, v48, v49
	v_cvt_pk_bf16_f32 v49, v0, v1
	global_store_dwordx2 v[200:201], v[52:53], off
	global_store_dwordx2 v[202:203], v[48:49], off
	s_cbranch_scc0 .LBB0_1370
	s_andn2_b64 vcc, exec, s[6:7]
	s_cbranch_vccnz .LBB0_1354
	s_add_u32 s0, s28, s14
	s_addc_u32 s1, s29, s15
	v_lshl_add_u64 v[0:1], v[112:113], 2, s[0:1]
	s_waitcnt vmcnt(2)
	v_lshl_add_u64 v[4:5], v[0:1], 0, v[76:77]
	global_store_dword v[4:5], v44, off nt
	v_lshl_add_u64 v[4:5], v[0:1], 0, v[78:79]
	global_store_dword v[4:5], v45, off nt
	v_lshl_add_u64 v[4:5], v[0:1], 0, v[80:81]
	global_store_dword v[4:5], v46, off nt
	v_lshl_add_u64 v[4:5], v[0:1], 0, v[82:83]
	global_store_dword v[4:5], v47, off nt
	v_lshl_add_u64 v[4:5], v[0:1], 0, v[84:85]
	global_store_dword v[4:5], v40, off nt
	v_lshl_add_u64 v[4:5], v[0:1], 0, v[86:87]
	global_store_dword v[4:5], v41, off nt
	v_lshl_add_u64 v[4:5], v[0:1], 0, v[88:89]
	global_store_dword v[4:5], v42, off nt
	v_lshl_add_u64 v[4:5], v[0:1], 0, v[90:91]
	global_store_dword v[4:5], v43, off nt
	v_lshl_add_u64 v[4:5], v[0:1], 0, v[92:93]
	global_store_dword v[4:5], v36, off nt
	v_lshl_add_u64 v[4:5], v[0:1], 0, v[94:95]
	global_store_dword v[4:5], v37, off nt
	v_lshl_add_u64 v[4:5], v[0:1], 0, v[96:97]
	global_store_dword v[4:5], v38, off nt
	v_lshl_add_u64 v[4:5], v[0:1], 0, v[98:99]
	global_store_dword v[4:5], v39, off nt
	v_lshl_add_u64 v[4:5], v[0:1], 0, v[100:101]
	global_store_dword v[4:5], v32, off nt
	v_lshl_add_u64 v[4:5], v[0:1], 0, v[102:103]
	global_store_dword v[4:5], v33, off nt
	v_lshl_add_u64 v[4:5], v[0:1], 0, v[104:105]
	global_store_dword v[4:5], v34, off nt
	v_lshl_add_u64 v[4:5], v[0:1], 0, v[106:107]
	global_store_dword v[4:5], v35, off nt
	v_lshl_add_u64 v[4:5], v[0:1], 0, v[108:109]
	global_store_dword v[4:5], v28, off nt
	v_lshl_add_u64 v[4:5], v[0:1], 0, v[110:111]
	global_store_dword v[4:5], v29, off nt
	v_lshl_add_u64 v[4:5], v[0:1], 0, v[138:139]
	global_store_dword v[4:5], v30, off nt
	v_lshl_add_u64 v[4:5], v[0:1], 0, v[136:137]
	global_store_dword v[4:5], v31, off nt
	v_lshl_add_u64 v[4:5], v[0:1], 0, v[134:135]
	global_store_dword v[4:5], v24, off nt
	v_lshl_add_u64 v[4:5], v[0:1], 0, v[132:133]
	global_store_dword v[4:5], v25, off nt
	v_lshl_add_u64 v[4:5], v[0:1], 0, v[130:131]
	global_store_dword v[4:5], v26, off nt
	v_lshl_add_u64 v[4:5], v[0:1], 0, v[128:129]
	global_store_dword v[4:5], v27, off nt
	v_lshl_add_u64 v[4:5], v[0:1], 0, v[126:127]
	global_store_dword v[4:5], v20, off nt
	v_lshl_add_u64 v[4:5], v[0:1], 0, v[124:125]
	global_store_dword v[4:5], v21, off nt
	v_lshl_add_u64 v[4:5], v[0:1], 0, v[122:123]
	global_store_dword v[4:5], v22, off nt
	v_lshl_add_u64 v[4:5], v[0:1], 0, v[120:121]
	global_store_dword v[4:5], v23, off nt
	v_lshl_add_u64 v[4:5], v[0:1], 0, v[118:119]
	global_store_dword v[4:5], v16, off nt
	v_lshl_add_u64 v[4:5], v[0:1], 0, v[116:117]
	global_store_dword v[4:5], v17, off nt
	v_lshl_add_u64 v[4:5], v[0:1], 0, v[114:115]
	v_lshl_add_u64 v[0:1], v[0:1], 0, v[140:141]
	global_store_dword v[4:5], v18, off nt
	global_store_dword v[0:1], v19, off nt
	s_branch .LBB0_1354
